# attention phase static priority on waves 0-3 instead of 4-7 (toggles deleted)
# speedup vs baseline: 1.0060x; 1.0005x over previous
; __global__ void __launch_bounds__(512, 2) fwd_kernel(Args a) {
;     ...
;     if (IN(2)) {
;         AttnP P; P.QA = (const bf16_t*)(ws + WS_QA); P.KA = (const bf16_t*)(ws + WS_KA); P.VAT = (const bf16_t*)(ws + WS_VAT); P.ZA = (const bf16_t*)(ws + WS_ZA);
;         P.QB = (const bf16_t*)(ws + WS_QB); P.KB = (const bf16_t*)(ws + WS_KB); P.VBT = (const bf16_t*)(ws + WS_VBT); P.ZB = (const bf16_t*)(ws + WS_ZB);
;         P.Y = (bf16_t*)(ws + WS_Y); P.sink = a.in[9]; P.rpb = a.in[6];
.LBB0_266:
	s_cmp_lt_i32 s66, 3
	s_cselect_b64 s[4:5], -1, 0
	s_and_b64 s[72:73], s[4:5], s[0:1]
	s_andn2_b64 vcc, exec, s[72:73]
	s_cbranch_vccnz .LBB0_427
	v_readfirstlane_b32 s100, v190
	s_nop 0
	s_cmp_lt_u32 s100, 0x100
	s_cbranch_scc0 .Lpbprio_lo
	s_setprio 1
